# prompt stick-breaking units: steps after the diagonal one use a hand-written unmasked body, the 8 gate loads of the unit tail are issued in the unit prologue
# baseline (speedup 1.0000x reference)
; #define LDS_AS __attribute__((address_space(3)))
; DI void prompt_sb_unit(const Params& p, int b, int h, int qt, char* smem) {
;     int tid_ = threadIdx.x; asm volatile("" : "+v"(tid_));
;     const int tid = tid_, lane = tid & 63, wave = tid >> 6, l31 = lane & 31, hh = lane >> 5;
;     LDS_AS char* lb = (LDS_AS char*)smem + wave * 9216;
;     const int wq0 = qt * 256 + 32 * wave, qpos = wq0 + l31;
;     const int qcol = h * 64, kcol = qcol + 512, vcol = qcol + 1024, gcol = qcol + 1536;
;     const size_t rowb = (size_t)b * LPAD;
;     __syncthreads();
;     if (wq0 < LP) {
;         bf16x8 q[4];
;         {
;             const bf16_t* qp = p.u + (rowb + qpos) * NU + qcol + 8 * hh;
; #pragma unroll
;             for (int s = 0; s < 4; ++s) q[s] = *(const bf16x8*)(qp + 16 * s);
;         }
;         AttnState st;
; #pragma unroll
;         for (int i = 0; i < 16; ++i) { st.o0[i] = 0.f; st.o1[i] = 0.f; }
;         st.m = -1e30f; st.l = 0.f;
;         u32x4 rk[4], rv[4];
;         const int r0 = lane >> 3, c0 = lane & 7;
;         const bf16_t* ub = p.u + (rowb + r0) * NU + c0 * 8;
;         int kp = wq0;
;         {
;             const bf16_t* kb = ub + (size_t)kp * NU;
; #pragma unroll
;             for (int i = 0; i < 4; ++i) { rk[i] = *(const u32x4*)(kb + (size_t)(8 * i) * NU + kcol); rv[i] = *(const u32x4*)(kb + (size_t)(8 * i) * NU + vcol); }
;         }
.LBB0_424:
	s_or_b64 exec, exec, s[0:1]
	v_mov_b32_e32 v0, s63
	s_waitcnt lgkmcnt(0)
	s_barrier
	ds_read_b32 v0, v0
	s_mov_b64 s[0:1], -1
	s_waitcnt lgkmcnt(0)
	v_cmp_lt_i32_e32 vcc, s66, v0
	v_readfirstlane_b32 s4, v0
	s_cbranch_vccnz .LBB0_419
	v_mov_b32_e32 v3, v138
	s_lshl_b32 s0, s4, 3
	v_ashrrev_i32_e32 v4, 6, v3
	s_and_b32 s0, s0, 0xffffff00
	v_lshlrev_b32_e32 v2, 5, v4
	s_waitcnt vmcnt(13)
	v_subrev_u32_e32 v104, s0, v2
	v_add_u32_e32 v0, 0x1000, v104
	v_cmp_gt_i32_e32 vcc, s88, v0
	s_barrier
	s_and_saveexec_b64 s[6:7], vcc
	s_cbranch_execz .LBB0_418
	v_and_b32_e32 v5, 31, v3
	v_or_b32_e32 v98, v0, v5
	s_bfe_u32 s1, s4, 0x20003
	s_mul_i32 s10, s1, 0x1040
	v_ashrrev_i32_e32 v99, 31, v98
	s_lshl_b32 s1, s4, 6
	v_lshl_add_u64 v[96:97], v[98:99], 0, s[10:11]
	s_and_b32 s39, s1, 0x1c0
	v_lshlrev_b64 v[6:7], 13, v[96:97]
	v_bfe_u32 v12, v3, 5, 1
	v_lshl_add_u64 v[6:7], s[68:69], 0, v[6:7]
	s_lshl_b32 s4, s39, 1
	s_mov_b32 s5, s11
	v_lshl_add_u64 v[100:101], v[6:7], 0, s[4:5]
	v_lshlrev_b32_e32 v130, 4, v12
	v_bfe_u32 v13, v3, 3, 3
	v_lshl_add_u64 v[6:7], v[100:101], 0, v[130:131]
	v_or_b32_e32 v1, s10, v13
	global_load_dwordx4 v[48:51], v[6:7], off
	global_load_dwordx4 v[52:55], v[6:7], off offset:32
	global_load_dwordx4 v[56:59], v[6:7], off offset:64
	global_load_dwordx4 v[60:63], v[6:7], off offset:96
	v_lshlrev_b32_e32 v6, 13, v1
	v_mov_b32_e32 v7, v131
	v_lshlrev_b32_e32 v1, 4, v3
	v_lshl_add_u64 v[6:7], s[68:69], 0, v[6:7]
	v_and_b32_e32 v8, 0x70, v1
	v_mov_b32_e32 v9, v131
	v_ashrrev_i32_e32 v1, 31, v0
	v_lshl_add_u64 v[102:103], v[6:7], 0, v[8:9]
	v_lshlrev_b64 v[0:1], 13, v[0:1]
	v_lshl_add_u64 v[0:1], v[102:103], 0, v[0:1]
	s_or_b32 s1, s39, 0x400
	s_or_b32 s30, s39, 0x200
	v_lshl_add_u64 v[6:7], v[0:1], 0, s[4:5]
	global_load_dwordx4 v[64:67], v[6:7], off offset:1024
	global_load_dwordx4 v[68:71], v[6:7], off offset:2048
	v_lshl_add_u64 v[6:7], v[0:1], 0, s[14:15]
	s_lshl_b32 s10, s30, 1
	s_lshl_b32 s4, s1, 1
	v_lshl_add_u64 v[10:11], v[6:7], 0, s[10:11]
	v_lshl_add_u64 v[6:7], v[6:7], 0, s[4:5]
	global_load_dwordx4 v[72:75], v[10:11], off
	global_load_dwordx4 v[76:79], v[6:7], off
	v_lshl_add_u64 v[6:7], v[0:1], 0, s[16:17]
	v_lshl_add_u64 v[10:11], v[6:7], 0, s[10:11]
	v_lshl_add_u64 v[6:7], v[6:7], 0, s[4:5]
	v_lshl_add_u64 v[0:1], v[0:1], 0, s[20:21]
	global_load_dwordx4 v[80:83], v[10:11], off
	global_load_dwordx4 v[84:87], v[6:7], off
	v_lshl_add_u64 v[6:7], v[0:1], 0, s[10:11]
	v_lshl_add_u64 v[0:1], v[0:1], 0, s[4:5]
	global_load_dwordx4 v[88:91], v[6:7], off
	global_load_dwordx4 v[92:95], v[0:1], off
	s_movk_i32 s4, 0x2400
	v_and_b32_e32 v1, 63, v3
	v_mul_lo_u32 v0, v4, s4
	v_lshlrev_b32_e32 v99, 2, v12
	v_cmp_gt_u32_e32 vcc, 32, v1
	v_lshrrev_b32_e32 v1, 2, v3
	v_and_b32_e32 v6, 16, v3
	v_lshlrev_b32_e32 v3, 2, v3
	v_add_u32_e32 v0, 0x100, v0
	v_and_or_b32 v1, v1, 3, v99
	v_and_or_b32 v3, v3, 12, v6
	v_add_u32_e32 v4, v0, v8
	v_mad_u32_u24 v5, v5, s89, v0
	v_mad_u32_u24 v0, v1, s89, v0
	v_lshlrev_b32_e32 v1, 1, v3
	v_mul_u32_u24_e32 v3, 0x90, v13
	v_add_u32_e32 v2, v2, v99
	v_mov_b32_e32 v106, 0
	v_subrev_u32_e32 v105, s0, v2
	s_mov_b32 s42, 0
	s_mov_b64 s[8:9], 0
	v_add_u32_e32 v107, v4, v3
	s_lshl_b32 s30, s30, 1
	s_lshl_b32 s34, s1, 1
	s_waitcnt vmcnt(24)
	v_add_u32_e32 v108, v5, v130
	v_add_u32_e32 v109, v0, v1
	v_mov_b32_e32 v0, 0
	v_mov_b32_e32 v1, v106
	v_mov_b32_e32 v2, v106
	v_mov_b32_e32 v3, v106
	v_mov_b32_e32 v4, v106
	v_mov_b32_e32 v5, v106
	v_mov_b32_e32 v6, v106
	v_mov_b32_e32 v7, v106
	v_mov_b32_e32 v8, v106
	v_mov_b32_e32 v9, v106
	v_mov_b32_e32 v10, v106
	v_mov_b32_e32 v11, v106
	v_mov_b32_e32 v12, v106
	v_mov_b32_e32 v13, v106
	v_mov_b32_e32 v14, v106
	v_mov_b32_e32 v15, v106
	v_mov_b32_e32 v16, 0
	v_mov_b32_e32 v17, v106
	v_mov_b32_e32 v18, v106
	v_mov_b32_e32 v19, v106
	v_mov_b32_e32 v20, v106
	v_mov_b32_e32 v21, v106
	v_mov_b32_e32 v22, v106
	v_mov_b32_e32 v23, v106
	v_mov_b32_e32 v24, v106
	v_mov_b32_e32 v25, v106
	v_mov_b32_e32 v26, v106
	v_mov_b32_e32 v27, v106
	v_mov_b32_e32 v28, v106
	v_mov_b32_e32 v29, v106
	v_mov_b32_e32 v30, v106
	v_mov_b32_e32 v31, v106
	v_lshlrev_b32_e32 v130, 1, v99
	v_lshl_add_u64 v[32:33], v[100:101], 0, v[130:131]
	global_load_dwordx2 v[148:149], v[32:33], off offset:3072
	global_load_dwordx2 v[150:151], v[32:33], off offset:3088
	global_load_dwordx2 v[152:153], v[32:33], off offset:3104
	global_load_dwordx2 v[154:155], v[32:33], off offset:3120
	global_load_dwordx2 v[156:157], v[32:33], off offset:3136
	global_load_dwordx2 v[158:159], v[32:33], off offset:3152
	global_load_dwordx2 v[160:161], v[32:33], off offset:3168
	global_load_dwordx2 v[162:163], v[32:33], off offset:3184
	s_branch .LBB0_428

; DI unsigned pk2(float a, float b) { f32x2 v = {a, b}; bf16x2v r = __builtin_convertvector(v, bf16x2v); return __builtin_bit_cast(unsigned, r); }
; DI float bflo(unsigned w) { return __uint_as_float(w << 16); }
; DI float bfhi(unsigned w) { return __uint_as_float(w & 0xffff0000u); }
; DI void store_gated(const AttnState& st, const bf16_t* sg, bf16_t* mo, int hh) {
; #pragma unroll
;     for (int dt = 0; dt < 2; ++dt)
; #pragma unroll
;         for (int g = 0; g < 4; ++g) {
;             const int d = 32 * dt + 8 * g + 4 * hh;
;             const u32x2 gv = *(const u32x2*)(sg + d);
;             const f32x16& o = dt == 0 ? st.o0 : st.o1;
;             const float a0 = o[4 * g] * bflo(gv[0]), a1 = o[4 * g + 1] * bfhi(gv[0]), a2 = o[4 * g + 2] * bflo(gv[1]), a3 = o[4 * g + 3] * bfhi(gv[1]);
;             *(u32x2*)(mo + d) = (u32x2){pk2(a0, a1), pk2(a2, a3)};
;         }
; }
; DI void prompt_sb_unit(const Params& p, int b, int h, int qt, char* smem) {
;     ...
;         if (qpos < LP) store_gated(st, p.u + (rowb + qpos) * NU + gcol, p.mix + (rowb + qpos) * DM + h * 64, hh);
.LBB0_432:
	s_or_b64 exec, exec, s[8:9]
	v_cmp_gt_i32_e32 vcc, s88, v98
	s_and_saveexec_b64 s[0:1], vcc
	s_xor_b64 s[0:1], exec, s[0:1]
	s_cbranch_execz .LBB0_418
	v_lshlrev_b32_e32 v130, 1, v99
	v_lshl_add_u64 v[32:33], v[100:101], 0, v[130:131]
	s_waitcnt vmcnt(8)
	v_lshlrev_b64 v[36:37], 11, v[96:97]
	s_lshl_b32 s10, s39, 1
	v_lshl_add_u64 v[36:37], s[70:71], 0, v[36:37]
	v_lshl_add_u64 v[36:37], v[36:37], 0, s[10:11]
	v_lshl_add_u64 v[36:37], v[36:37], 0, v[130:131]
	v_lshlrev_b32_e32 v56, 16, v148
	v_and_b32_e32 v57, 0xffff0000, v148
	v_lshlrev_b32_e32 v58, 16, v149
	v_and_b32_e32 v59, 0xffff0000, v149
	v_pk_mul_f32 v[16:17], v[16:17], v[56:57]
	v_pk_mul_f32 v[18:19], v[18:19], v[58:59]
	v_cvt_pk_bf16_f32 v16, v16, v17
	v_cvt_pk_bf16_f32 v17, v18, v19
	global_store_dwordx2 v[36:37], v[16:17], off
	v_lshlrev_b32_e32 v60, 16, v150
	v_and_b32_e32 v61, 0xffff0000, v150
	v_lshlrev_b32_e32 v62, 16, v151
	v_and_b32_e32 v63, 0xffff0000, v151
	v_pk_mul_f32 v[20:21], v[20:21], v[60:61]
	v_pk_mul_f32 v[22:23], v[22:23], v[62:63]
	v_cvt_pk_bf16_f32 v20, v20, v21
	v_cvt_pk_bf16_f32 v21, v22, v23
	global_store_dwordx2 v[36:37], v[20:21], off offset:16
	v_lshlrev_b32_e32 v56, 16, v152
	v_and_b32_e32 v57, 0xffff0000, v152
	v_lshlrev_b32_e32 v58, 16, v153
	v_and_b32_e32 v59, 0xffff0000, v153
	v_pk_mul_f32 v[24:25], v[24:25], v[56:57]
	v_pk_mul_f32 v[26:27], v[26:27], v[58:59]
	v_cvt_pk_bf16_f32 v24, v24, v25
	v_cvt_pk_bf16_f32 v25, v26, v27
	global_store_dwordx2 v[36:37], v[24:25], off offset:32
	v_lshlrev_b32_e32 v60, 16, v154
	v_and_b32_e32 v61, 0xffff0000, v154
	v_lshlrev_b32_e32 v62, 16, v155
	v_and_b32_e32 v63, 0xffff0000, v155
	v_pk_mul_f32 v[28:29], v[28:29], v[60:61]
	v_pk_mul_f32 v[30:31], v[30:31], v[62:63]
	v_cvt_pk_bf16_f32 v28, v28, v29
	v_cvt_pk_bf16_f32 v29, v30, v31
	global_store_dwordx2 v[36:37], v[28:29], off offset:48
	v_lshlrev_b32_e32 v56, 16, v156
	v_and_b32_e32 v57, 0xffff0000, v156
	v_lshlrev_b32_e32 v58, 16, v157
	v_and_b32_e32 v59, 0xffff0000, v157
	v_pk_mul_f32 v[0:1], v[0:1], v[56:57]
	v_pk_mul_f32 v[2:3], v[2:3], v[58:59]
	v_cvt_pk_bf16_f32 v0, v0, v1
	v_cvt_pk_bf16_f32 v1, v2, v3
	global_store_dwordx2 v[36:37], v[0:1], off offset:64
	v_lshlrev_b32_e32 v60, 16, v158
	v_and_b32_e32 v61, 0xffff0000, v158
	v_lshlrev_b32_e32 v62, 16, v159
	v_and_b32_e32 v63, 0xffff0000, v159
	v_pk_mul_f32 v[4:5], v[4:5], v[60:61]
	v_pk_mul_f32 v[6:7], v[6:7], v[62:63]
	v_cvt_pk_bf16_f32 v4, v4, v5
	v_cvt_pk_bf16_f32 v5, v6, v7
	global_store_dwordx2 v[36:37], v[4:5], off offset:80
	v_lshlrev_b32_e32 v56, 16, v160
	v_and_b32_e32 v57, 0xffff0000, v160
	v_lshlrev_b32_e32 v58, 16, v161
	v_and_b32_e32 v59, 0xffff0000, v161
	v_pk_mul_f32 v[8:9], v[8:9], v[56:57]
	v_pk_mul_f32 v[10:11], v[10:11], v[58:59]
	v_cvt_pk_bf16_f32 v8, v8, v9
	v_cvt_pk_bf16_f32 v9, v10, v11
	global_store_dwordx2 v[36:37], v[8:9], off offset:96
	v_lshlrev_b32_e32 v60, 16, v162
	v_and_b32_e32 v61, 0xffff0000, v162
	v_lshlrev_b32_e32 v62, 16, v163
	v_and_b32_e32 v63, 0xffff0000, v163
	v_pk_mul_f32 v[12:13], v[12:13], v[60:61]
	v_pk_mul_f32 v[14:15], v[14:15], v[62:63]
	v_cvt_pk_bf16_f32 v12, v12, v13
	v_cvt_pk_bf16_f32 v13, v14, v15
	global_store_dwordx2 v[36:37], v[12:13], off offset:112
	s_branch .LBB0_418
